# code placement: MLA/GQA/NA attention loop heads aligned to 64 bytes (on top of K-loop alignment)
# baseline (speedup 1.0000x reference)
; template <int DQK, int LDK> ...
;     ...
;   int tid_ = threadIdx.x; asm volatile("" : "+v"(tid_));
;   const int tid = tid_, wid = __builtin_amdgcn_readfirstlane(tid >> 6), lane = tid & 63, r32 = lane & 31, hi = lane >> 5;
;   char* QRw = lds + OFF_QR + wid * 4608;
;   bf16_t* V_lds = (bf16_t*)lds; bf16_t* K_lds = (bf16_t*)(lds + OFF_K); char* KR_lds = lds + OFF_KR;
;   float* ws = (float*)(lds + OFF_WS) + wid * 64; float* li_l = ws; float* al_l = ws + 32;
;   float m_reg = -1e30f, l_reg = 0; f32x16 o[4] = {}; bf16x8 qr[NQ];
;   const bf16_t* Qw = Qb + (long)(wid * QBLK + r32) * LDQ + hi * 8;
; #pragma unroll
;   for (int d0 = 0; d0 < NQ; ++d0) qr[d0] = *reinterpret_cast<const bf16x8*>(Qw + d0 * 16);
;   if constexpr (ROPE) {
;     const int pos = qpos0 + wid * QBLK + r32;
; #pragma unroll
;     for (int d = 0; d < 2; ++d) {
;       const float* cp = COS + pos * 32 + d * 16 + hi * 8; const float* sp = SIN + pos * 32 + d * 16 + hi * 8;
;       const f32x4 c0 = *(const f32x4*)cp, c1 = *(const f32x4*)(cp + 4), s0 = *(const f32x4*)sp, s1 = *(const f32x4*)(sp + 4);
;       const bf16x8 a = *reinterpret_cast<const bf16x8*>(Qw + (8 + d) * 16), b = *reinterpret_cast<const bf16x8*>(Qw + (10 + d) * 16);
;       float y1[8], y2[8];
; #pragma unroll
;       for (int e = 0; e < 8; ++e) { const float c = e < 4 ? c0[e & 3] : c1[e & 3], s = e < 4 ? s0[e & 3] : s1[e & 3];
;         const float x1 = __uint_as_float(((unsigned)(unsigned short)a[e]) << 16), x2 = __uint_as_float(((unsigned)(unsigned short)b[e]) << 16);
;         y1[e] = x1 * c - x2 * s; y2[e] = x2 * c + x1 * s; }
;       u32x4 wa = {pk2(y1[0], y1[1]), pk2(y1[2], y1[3]), pk2(y1[4], y1[5]), pk2(y1[6], y1[7])};
;       u32x4 wb = {pk2(y2[0], y2[1]), pk2(y2[2], y2[3]), pk2(y2[4], y2[5]), pk2(y2[6], y2[7])};
; __global__ void __launch_bounds__(512) fwd_mega(Args a_kernarg) {
;     ...
;                     if (uu < 512) { qb = uu & 31; h = (uu >> 5) & 7; rowbase = HTOK + (uu >> 8) * 8192; seq = 8192; }
;                     else { const int u = uu - 512; qb = u & 7; h = (u >> 3) & 7; rowbase = (u >> 6) * 2048; seq = 2048; }
;                     const bf16_t* Kh = KV + (size_t)rowbase * 2048 + h * 256;
;     ...
;                     att::attn_unit<192, 2048>(Q + (size_t)(rowbase + qb * 256) * 1536 + h * 192, Kh, Kh + 128, KR + (size_t)rowbase * 64,
.LBB0_342:
	s_lshl_b32 s2, s7, 5
	s_cmpk_lt_i32 s7, 0x200
	s_cselect_b32 s5, 0xffffe000, s71
	s_movk_i32 s8, 0x4000
	s_cselect_b32 s3, 31, 7
	s_cselect_b32 s4, 5, 3
	s_cselect_b32 s8, s8, 0xffffc000
	s_cselect_b32 s15, 0x80, 32
	s_and_b32 s2, s2, s5
	s_and_b32 s14, s7, s3
	s_lshr_b32 s3, s7, s4
	s_add_i32 s2, s2, s8
	s_and_b32 s9, s3, 7
	s_ashr_i32 s3, s2, 31
	s_lshl_b64 s[4:5], s[2:3], 12
	v_readlane_b32 s16, v252, 29
	v_readlane_b32 s17, v252, 30
	s_add_u32 s4, s16, s4
	s_addc_u32 s5, s17, s5
	s_lshl_b32 s20, s9, 9
	s_add_u32 s16, s4, s20
	s_addc_u32 s17, s5, 0
	s_lshl_b32 s14, s14, 8
	s_add_i32 s34, s14, s2
	s_ashr_i32 s35, s34, 31
	s_mul_i32 s5, s34, 0xc00
	s_mul_hi_i32 s4, s34, 0xc00
	s_add_u32 s5, s56, s5
	s_addc_u32 s4, s57, s4
	s_mul_i32 s8, s9, 0x180
	s_add_u32 s28, s5, s8
	s_addc_u32 s29, s4, 0
	s_lshl_b64 s[4:5], s[2:3], 7
	v_readlane_b32 s8, v252, 39
	s_waitcnt vmcnt(0)
	v_mov_b32_e32 v56, v200
	s_add_u32 s18, s8, s4
	v_readlane_b32 s8, v252, 40
	s_addc_u32 s19, s8, s5
	v_readfirstlane_b32 s21, v56
	s_ashr_i32 s8, s21, 6
	v_and_b32_e32 v176, 31, v56
	s_lshl_b32 s26, s8, 5
	s_waitcnt vmcnt(4)
	v_or_b32_e32 v10, s14, v176
	v_add_lshl_u32 v10, v10, s26, 5
	v_ashrrev_i32_e32 v11, 31, v10
	v_readlane_b32 s24, v252, 3
	v_bfe_u32 v177, v56, 5, 1
	v_or_b32_e32 v0, s26, v176
	v_mov_b64_e32 v[2:3], s[28:29]
	v_lshlrev_b64 v[10:11], 2, v[10:11]
	v_readlane_b32 s25, v252, 4
	v_mad_i64_i32 v[2:3], s[28:29], v0, s23, v[2:3]
	v_lshlrev_b32_e32 v0, 4, v177
	v_lshl_add_u64 v[12:13], s[24:25], 0, v[10:11]
	v_readlane_b32 s24, v252, 5
	v_lshl_add_u64 v[50:51], v[2:3], 0, v[0:1]
	v_readlane_b32 s25, v252, 6
	global_load_dwordx4 v[2:5], v[50:51], off offset:256
	global_load_dwordx4 v[6:9], v[50:51], off offset:320
	s_waitcnt vmcnt(2)
	v_and_b32_e32 v14, 32, v56
	v_mov_b32_e32 v15, v1
	v_lshl_add_u64 v[10:11], s[24:25], 0, v[10:11]
	v_lshl_add_u64 v[46:47], v[10:11], 0, v[14:15]
	v_lshl_add_u64 v[38:39], v[12:13], 0, v[14:15]
	global_load_dwordx4 v[10:13], v[46:47], off
	global_load_dwordx4 v[14:17], v[38:39], off
	global_load_dwordx4 v[18:21], v[46:47], off offset:16
	global_load_dwordx4 v[22:25], v[38:39], off offset:16
	global_load_dwordx4 v[142:145], v[50:51], off
	global_load_dwordx4 v[134:137], v[50:51], off offset:32
	global_load_dwordx4 v[26:29], v[50:51], off offset:288
	global_load_dwordx4 v[30:33], v[50:51], off offset:352
	global_load_dwordx4 v[34:37], v[38:39], off offset:80
	s_nop 0
	global_load_dwordx4 v[38:41], v[38:39], off offset:64
	s_nop 0
	global_load_dwordx4 v[42:45], v[46:47], off offset:80
	s_nop 0
	global_load_dwordx4 v[46:49], v[46:47], off offset:64
	s_nop 0
	global_load_dwordx4 v[158:161], v[50:51], off offset:64
	global_load_dwordx4 v[154:157], v[50:51], off offset:96
	global_load_dwordx4 v[150:153], v[50:51], off offset:128
	global_load_dwordx4 v[146:149], v[50:51], off offset:160
	global_load_dwordx4 v[138:141], v[50:51], off offset:192
	global_load_dwordx4 v[130:133], v[50:51], off offset:224
	s_and_b32 s14, s21, 0x3fffffc0
	s_mul_i32 s21, s8, 0x1200
	s_add_i32 s21, s21, 0
	v_mul_u32_u24_e32 v57, 0x90, v176
	s_add_i32 s21, s21, 0x15800
	v_mov_b32_e32 v67, v1
	s_lshl_b32 s14, s14, 2
	s_add_i32 s14, s14, 0
	s_add_i32 s14, s14, 0x15000
	s_cmp_lg_u32 0, -1
	v_or_b32_e32 v83, 32, v0
	v_and_b32_e32 v178, 63, v56
	v_mad_u32_u24 v192, v176, s74, v83
	s_mov_b64 s[28:29], 0x40000
	s_mov_b64 s[24:25], 0x60000
	s_mov_b32 s76, s77
	s_mov_b32 s78, s77
	s_mov_b32 s79, s77
	s_mov_b32 s80, s77
	s_mov_b32 s81, s77
	s_mov_b32 s82, s77
	s_mov_b32 s83, s77
	s_mov_b32 s84, s77
	s_mov_b32 s85, s77
	s_mov_b32 s86, s77
	s_mov_b32 s87, s77
	s_mov_b32 s88, s77
	s_mov_b32 s89, s77
	s_mov_b32 s90, s77
	s_mov_b32 s91, s77
	v_cmp_gt_u32_e64 s[40:41], 32, v178
	v_lshl_add_u32 v179, v176, 2, s14
	v_mov_b32_e32 v180, 0
	s_waitcnt vmcnt(19)
	v_and_b32_e32 v51, 0xffff0000, v2
	v_lshlrev_b32_e32 v50, 16, v2
	v_and_b32_e32 v55, 0xffff0000, v3
	v_lshlrev_b32_e32 v54, 16, v3
	s_waitcnt vmcnt(18)
	v_and_b32_e32 v3, 0xffff0000, v7
	v_lshlrev_b32_e32 v2, 16, v7
	v_and_b32_e32 v59, 0xffff0000, v8
	v_lshlrev_b32_e32 v58, 16, v8
	s_waitcnt vmcnt(17)
	v_pk_mul_f32 v[62:63], v[12:13], v[2:3]
	s_waitcnt vmcnt(16)
	v_pk_mul_f32 v[2:3], v[16:17], v[2:3]
	v_and_b32_e32 v53, 0xffff0000, v6
	v_lshlrev_b32_e32 v52, 16, v6
	v_and_b32_e32 v7, 0xffff0000, v4
	v_lshlrev_b32_e32 v6, 16, v4
	s_waitcnt vmcnt(15)
	v_pk_mul_f32 v[64:65], v[18:19], v[58:59]
	s_waitcnt vmcnt(14)
	v_pk_mul_f32 v[58:59], v[22:23], v[58:59]
	v_pk_fma_f32 v[12:13], v[12:13], v[54:55], v[2:3]
	v_and_b32_e32 v3, 0xffff0000, v5
	v_lshlrev_b32_e32 v2, 16, v5
	v_and_b32_e32 v5, 0xffff0000, v9
	v_lshlrev_b32_e32 v4, 16, v9
	v_pk_mul_f32 v[60:61], v[10:11], v[52:53]
	v_pk_mul_f32 v[52:53], v[14:15], v[52:53]
	v_pk_fma_f32 v[22:23], v[22:23], v[6:7], v[64:65] neg_lo:[0,0,1] neg_hi:[0,0,1]
	v_pk_fma_f32 v[18:19], v[18:19], v[6:7], v[58:59]
	v_pk_mul_f32 v[6:7], v[20:21], v[4:5]
	v_pk_fma_f32 v[14:15], v[14:15], v[50:51], v[60:61] neg_lo:[0,0,1] neg_hi:[0,0,1]
	v_pk_fma_f32 v[10:11], v[10:11], v[50:51], v[52:53]
	v_pk_fma_f32 v[16:17], v[16:17], v[54:55], v[62:63] neg_lo:[0,0,1] neg_hi:[0,0,1]
	v_pk_fma_f32 v[6:7], v[24:25], v[2:3], v[6:7] neg_lo:[0,0,1] neg_hi:[0,0,1]
	v_pk_mul_f32 v[4:5], v[24:25], v[4:5]
	v_ashrrev_i32_e32 v50, 4, v56
	v_pk_fma_f32 v[20:21], v[20:21], v[2:3], v[4:5]
	v_cvt_pk_bf16_f32 v2, v14, v15
	v_cvt_pk_bf16_f32 v3, v16, v17
	v_cvt_pk_bf16_f32 v4, v22, v23
	v_cvt_pk_bf16_f32 v5, v6, v7
	v_add3_u32 v55, s21, v57, v0
	v_lshlrev_b32_e32 v57, 3, v56
	v_add_u32_e32 v62, 32, v50
	ds_write_b128 v55, v[2:5]
	v_and_b32_e32 v2, 0x78, v57
	v_ashrrev_i32_e32 v51, 31, v50
	v_ashrrev_i32_e32 v63, 31, v62
	v_lshlrev_b32_e32 v54, 1, v2
	v_ashrrev_i32_e32 v64, 3, v56
	v_lshlrev_b64 v[2:3], 12, v[50:51]
	v_lshlrev_b64 v[4:5], 12, v[62:63]
	v_or_b32_e32 v2, v2, v54
	v_or_b32_e32 v4, v4, v54
	v_ashrrev_i32_e32 v65, 31, v64
	v_lshl_add_u64 v[2:3], s[16:17], 0, v[2:3]
	v_lshl_add_u64 v[4:5], s[16:17], 0, v[4:5]
	v_and_b32_e32 v166, 56, v57
	v_lshlrev_b64 v[52:53], 7, v[64:65]
	v_cvt_pk_bf16_f32 v6, v10, v11
	v_cvt_pk_bf16_f32 v7, v12, v13
	v_cvt_pk_bf16_f32 v8, v18, v19
	v_cvt_pk_bf16_f32 v9, v20, v21
	global_load_dwordx4 v[10:13], v[2:3], off offset:256
	global_load_dwordx4 v[14:17], v[4:5], off offset:256
	global_load_dwordx4 v[18:21], v[2:3], off
	global_load_dwordx4 v[22:25], v[4:5], off
	v_lshl_add_u64 v[4:5], s[18:19], 0, v[52:53]
	v_lshlrev_b32_e32 v66, 1, v166
	v_lshl_add_u64 v[4:5], v[4:5], 0, v[66:67]
	global_load_dwordx4 v[58:61], v[4:5], off
	ds_write_b128 v55, v[6:9] offset:64
	s_waitcnt vmcnt(15)
; __device__ __forceinline__ unsigned pk2(float lo, float hi) { f32x2_t v = {lo, hi}; bf16x2_t b = __builtin_convertvector(v, bf16x2_t); return __builtin_bit_cast(unsigned, b); }
; __device__ __forceinline__ int v_st(int k, int c) { const int kk = (k & ~0xC) | ((k & 4) << 1) | ((k & 8) >> 1); return ((kk >> 3) * 4 + (c >> 5)) * 512 + ((kk & 7) * 32 + (c & 31)) * 2; }
; template <int DQK, int LDK> ...
;     ...
;   if constexpr (ROPE) {
;     const int pos = qpos0 + wid * QBLK + r32;
; #pragma unroll
;     for (int d = 0; d < 2; ++d) {
;       const float* cp = COS + pos * 32 + d * 16 + hi * 8; const float* sp = SIN + pos * 32 + d * 16 + hi * 8;
;       const f32x4 c0 = *(const f32x4*)cp, c1 = *(const f32x4*)(cp + 4), s0 = *(const f32x4*)sp, s1 = *(const f32x4*)(sp + 4);
;       const bf16x8 a = *reinterpret_cast<const bf16x8*>(Qw + (8 + d) * 16), b = *reinterpret_cast<const bf16x8*>(Qw + (10 + d) * 16);
;       float y1[8], y2[8];
; #pragma unroll
;       for (int e = 0; e < 8; ++e) { const float c = e < 4 ? c0[e & 3] : c1[e & 3], s = e < 4 ? s0[e & 3] : s1[e & 3];
;         const float x1 = __uint_as_float(((unsigned)(unsigned short)a[e]) << 16), x2 = __uint_as_float(((unsigned)(unsigned short)b[e]) << 16);
;         y1[e] = x1 * c - x2 * s; y2[e] = x2 * c + x1 * s; }
;       u32x4 wa = {pk2(y1[0], y1[1]), pk2(y1[2], y1[3]), pk2(y1[4], y1[5]), pk2(y1[6], y1[7])};
;       u32x4 wb = {pk2(y2[0], y2[1]), pk2(y2[2], y2[3]), pk2(y2[4], y2[5]), pk2(y2[6], y2[7])};
;       *(u32x4*)(QRw + KRSWZ(r32, (d * 16 + hi * 8) * 2)) = wa; *(u32x4*)(QRw + KRSWZ(r32, (32 + d * 16 + hi * 8) * 2)) = wb;
;     }
;   }
;   const int sr = tid >> 4, sc = (tid & 15) * 8, vst0 = v_st(sr, sc), vst1 = v_st(32 + sr, sc);
;   const int krr = tid >> 3, krc = (tid & 7) * 8;
;   const int vb0 = (int)(uintptr_t)V_lds + v_rd_base(lane);
;   constexpr int SD = ROPE ? 1 : 2;
;   struct { bf16x8 vs0, vs1, ks0, ks1, kr; } sr_[SD];
;     ...
;   f32x16 pA0, pA1, pB0, pB1; float mnA, mnB, alA, alB; bf16x8 pa0, pa1, pa2, pa3; const int NT = seq / KVBLK;
;   constexpr int SE = 0, SO = SD - 1;
;   SLOAD(SE, 0); asm volatile("s_waitcnt vmcnt(0)" ::: "memory"); SWRITE(0, SE); __syncthreads();
;   qkt<DQK>(pA0, pA1, K_lds, KR_lds, QRw, qr, r32, hi); partialSM<DQK>(pA0, pA1, m_reg, mnA, alA);
	v_and_b32_e32 v9, 0xffff0000, v30
	v_lshlrev_b32_e32 v8, 16, v30
	v_and_b32_e32 v7, 0xffff0000, v26
	v_lshlrev_b32_e32 v6, 16, v26
	s_waitcnt vmcnt(11)
	v_pk_mul_f32 v[68:69], v[46:47], v[8:9]
	v_pk_mul_f32 v[8:9], v[38:39], v[8:9]
	v_pk_fma_f32 v[68:69], v[38:39], v[6:7], v[68:69] neg_lo:[0,0,1] neg_hi:[0,0,1]
	v_pk_fma_f32 v[38:39], v[46:47], v[6:7], v[8:9]
	v_and_b32_e32 v9, 0xffff0000, v31
	v_lshlrev_b32_e32 v8, 16, v31
	v_and_b32_e32 v7, 0xffff0000, v27
	v_lshlrev_b32_e32 v6, 16, v27
	v_pk_mul_f32 v[26:27], v[48:49], v[8:9]
	v_pk_mul_f32 v[8:9], v[40:41], v[8:9]
	v_pk_fma_f32 v[26:27], v[40:41], v[6:7], v[26:27] neg_lo:[0,0,1] neg_hi:[0,0,1]
	v_pk_fma_f32 v[30:31], v[48:49], v[6:7], v[8:9]
	v_and_b32_e32 v9, 0xffff0000, v32
	v_lshlrev_b32_e32 v8, 16, v32
	v_and_b32_e32 v7, 0xffff0000, v28
	v_lshlrev_b32_e32 v6, 16, v28
	v_pk_mul_f32 v[40:41], v[42:43], v[8:9]
	v_pk_mul_f32 v[8:9], v[34:35], v[8:9]
	v_pk_fma_f32 v[40:41], v[34:35], v[6:7], v[40:41] neg_lo:[0,0,1] neg_hi:[0,0,1]
	v_pk_fma_f32 v[34:35], v[42:43], v[6:7], v[8:9]
	v_and_b32_e32 v9, 0xffff0000, v33
	v_lshlrev_b32_e32 v8, 16, v33
	v_and_b32_e32 v7, 0xffff0000, v29
	v_lshlrev_b32_e32 v6, 16, v29
	v_pk_mul_f32 v[28:29], v[44:45], v[8:9]
	v_pk_mul_f32 v[8:9], v[36:37], v[8:9]
	v_pk_fma_f32 v[28:29], v[36:37], v[6:7], v[28:29] neg_lo:[0,0,1] neg_hi:[0,0,1]
	v_pk_fma_f32 v[32:33], v[44:45], v[6:7], v[8:9]
	v_cvt_pk_bf16_f32 v6, v68, v69
	v_cvt_pk_bf16_f32 v7, v26, v27
	v_cvt_pk_bf16_f32 v8, v40, v41
	v_cvt_pk_bf16_f32 v9, v28, v29
	v_cvt_pk_bf16_f32 v26, v38, v39
	v_cvt_pk_bf16_f32 v27, v30, v31
	v_cvt_pk_bf16_f32 v28, v34, v35
	v_cvt_pk_bf16_f32 v29, v32, v33
	ds_write_b128 v55, v[6:9] offset:32
	ds_write_b128 v55, v[26:29] offset:96
	v_and_b32_e32 v6, 0xfffff0, v50
	v_lshlrev_b32_e32 v7, 1, v50
	v_and_b32_e32 v26, 0xfffff0, v62
	v_lshlrev_b32_e32 v27, 1, v62
	v_and_or_b32 v6, v7, 8, v6
	v_and_or_b32 v26, v27, 8, v26
	v_lshrrev_b32_e32 v7, 1, v50
	v_lshrrev_b32_e32 v6, 1, v6
	v_bfe_u32 v8, v57, 5, 2
	v_and_b32_e32 v9, 3, v50
	v_lshrrev_b32_e32 v26, 1, v26
	v_or_b32_e32 v6, v6, v8
	v_and_or_b32 v7, v7, 4, v9
	v_or_b32_e32 v8, v26, v8
	v_lshlrev_b32_e32 v6, 9, v6
	v_lshlrev_b32_e32 v7, 6, v7
	v_and_b32_e32 v9, 48, v54
	v_lshlrev_b32_e32 v8, 9, v8
	v_or3_b32 v6, v6, v7, v9
	v_or3_b32 v7, v8, v7, v9
	v_add_u32_e32 v185, 0, v6
	v_add_u32_e32 v186, 0, v7
	v_mad_u64_u32 v[6:7], s[18:19], v50, s75, v[54:55]
	v_mad_u64_u32 v[54:55], s[18:19], v64, s74, v[66:67]
	s_cselect_b32 s17, 0, 0
	s_add_i32 s18, 0, 0x10800
	v_mad_u32_u24 v55, v176, s75, v0
	v_add_u32_e32 v187, 0, v6
	v_add_u32_e32 v6, s18, v54
	v_add_u32_e32 v183, 0, v55
	s_waitcnt vmcnt(0)
	s_waitcnt vmcnt(4)
	ds_write_b128 v185, v[10:13]
	s_waitcnt vmcnt(3)
	ds_write_b128 v186, v[14:17]
	s_waitcnt vmcnt(2)
	ds_write_b128 v187, v[18:21] offset:32768
	s_waitcnt vmcnt(1)
	ds_write_b128 v187, v[22:25] offset:41472
	v_lshlrev_b32_e32 v57, 3, v178
	s_waitcnt vmcnt(0)
	ds_write_b128 v6, v[58:61]
	s_waitcnt lgkmcnt(0)
	s_barrier
	ds_read_b128 v[6:9], v183 offset:32768
	ds_read_b128 v[10:13], v183 offset:32800
	s_waitcnt lgkmcnt(1)
	v_mfma_f32_32x32x16_bf16 v[18:33], v[6:9], v[142:145], 0
	ds_read_b128 v[6:9], v183 offset:41472
	ds_read_b128 v[14:17], v183 offset:41504
	v_add_u32_e32 v193, s18, v192
	s_mov_b32 s19, 0x40000
	v_add_u32_e32 v218, 0, v54
	v_add_u32_e32 v219, 0x12c00, v218
	v_lshl_add_u64 v[168:169], v[52:53], 0, s[4:5]
	s_mov_b32 s16, 2
	s_waitcnt lgkmcnt(1)
	v_mfma_f32_32x32x16_bf16 v[34:49], v[6:9], v[142:145], 0
	v_mfma_f32_32x32x16_bf16 v[18:33], v[10:13], v[134:137], v[18:33]
	ds_read_b128 v[6:9], v183 offset:32832
	ds_read_b128 v[10:13], v183 offset:32864
	s_waitcnt lgkmcnt(2)
	v_mfma_f32_32x32x16_bf16 v[34:49], v[14:17], v[134:137], v[34:49]
	s_waitcnt lgkmcnt(1)
	v_mfma_f32_32x32x16_bf16 v[18:33], v[6:9], v[158:161], v[18:33]
	ds_read_b128 v[6:9], v183 offset:41536
	ds_read_b128 v[14:17], v183 offset:41568
	s_waitcnt lgkmcnt(1)
	v_mfma_f32_32x32x16_bf16 v[34:49], v[6:9], v[158:161], v[34:49]
	v_mfma_f32_32x32x16_bf16 v[18:33], v[10:13], v[154:157], v[18:33]
	ds_read_b128 v[6:9], v183 offset:32896
	ds_read_b128 v[10:13], v183 offset:32928
	s_waitcnt lgkmcnt(2)
	v_mfma_f32_32x32x16_bf16 v[34:49], v[14:17], v[154:157], v[34:49]
	s_waitcnt lgkmcnt(1)
	v_mfma_f32_32x32x16_bf16 v[18:33], v[6:9], v[150:153], v[18:33]
	ds_read_b128 v[6:9], v183 offset:41600
	ds_read_b128 v[14:17], v183 offset:41632
	s_waitcnt lgkmcnt(1)
	v_mfma_f32_32x32x16_bf16 v[34:49], v[6:9], v[150:153], v[34:49]
	v_mfma_f32_32x32x16_bf16 v[18:33], v[10:13], v[146:149], v[18:33]
	ds_read_b128 v[6:9], v183 offset:32960
	ds_read_b128 v[10:13], v183 offset:32992
	s_waitcnt lgkmcnt(2)
	v_mfma_f32_32x32x16_bf16 v[34:49], v[14:17], v[146:149], v[34:49]
	s_waitcnt lgkmcnt(1)
	v_mfma_f32_32x32x16_bf16 v[18:33], v[6:9], v[138:141], v[18:33]
	ds_read_b128 v[6:9], v183 offset:41664
	ds_read_b128 v[14:17], v183 offset:41696
	s_waitcnt lgkmcnt(1)
	v_mfma_f32_32x32x16_bf16 v[34:49], v[6:9], v[138:141], v[34:49]
	v_lshlrev_b32_e32 v6, 7, v176
	v_sub_u32_e32 v188, v55, v6
	v_add_u32_e32 v189, s18, v188
	ds_read_b128 v[6:9], v189
	v_mad_u32_u24 v55, v176, s74, v204
	v_add_u32_e32 v184, s21, v188
	v_add_u32_e32 v190, v55, v0
	v_mfma_f32_32x32x16_bf16 v[18:33], v[10:13], v[130:133], v[18:33]
	ds_read_b128 v[10:13], v184
	v_add_u32_e32 v191, s18, v190
	v_add_u32_e32 v198, v83, v55
	v_add_u32_e32 v199, s18, v198
	s_mov_b32 s21, 0x42ddb3d8
	s_waitcnt lgkmcnt(2)
	v_mfma_f32_32x32x16_bf16 v[34:49], v[14:17], v[130:133], v[34:49]
	ds_read_b128 v[14:17], v191
	ds_read_b128 v[58:61], v184 offset:32
	s_waitcnt lgkmcnt(2)
; #define SWAIT() do { if constexpr (SD == 1) asm volatile("s_waitcnt vmcnt(0)" ::: "memory"); else asm volatile("s_waitcnt vmcnt(4)" ::: "memory"); } while (0)
; template <int DQK> __device__ __forceinline__ void partialSM(f32x16& p0, f32x16& p1, float& m_reg, float& mn, float& alpha) {
;   constexpr float SCALE = (DQK == 192) ? 0.07216878364870322f : (DQK == 64 ? 1.0f : 0.08838834764831845f);
;   constexpr float C = SCALE * 1.4426950408889634f;
;   float pmax = p0[0];
; #pragma unroll
;   for (int r = 1; r < 16; ++r) pmax = fmaxf(pmax, p0[r]);
; #pragma unroll
;   for (int r = 0; r < 16; ++r) pmax = fmaxf(pmax, p1[r]);
;   { auto rr = __builtin_amdgcn_permlane32_swap(__float_as_uint(pmax), __float_as_uint(pmax), false, false);
;     pmax = fmaxf(__uint_as_float(rr[0]), __uint_as_float(rr[1])); }
;   if (__builtin_expect(__all(pmax - m_reg <= THR / SCALE), 1)) { mn = m_reg; alpha = 1.f; }
;   else { mn = fmaxf(m_reg, pmax); alpha = __builtin_amdgcn_exp2f((m_reg - mn) * C); m_reg = mn; }
;   float mnC = -mn * C;
; #pragma unroll
;   for (int r = 0; r < 16; ++r) p0[r] = fmaf(p0[r], C, mnC);
; #pragma unroll
;   for (int r = 0; r < 16; ++r) p1[r] = fmaf(p1[r], C, mnC);
; #pragma unroll
;   for (int r = 0; r < 16; ++r) p0[r] = __builtin_amdgcn_exp2f(p0[r]);
; }
; template <int DQK, int LDK> ...
;     ...
;   qkt<DQK>(pA0, pA1, K_lds, KR_lds, QRw, qr, r32, hi); partialSM<DQK>(pA0, pA1, m_reg, mnA, alA);
;   SLOAD(SO, KVBLK); if constexpr (SD == 2) { if (2 < NT) SLOAD(SE, 2 * KVBLK); }
;   SWAIT(); SWRITE(1, SO); __syncthreads();
	v_mfma_f32_32x32x16_bf16 v[18:33], v[6:9], v[10:13], v[18:33]
	v_lshlrev_b32_e32 v6, 4, v56
	v_and_b32_e32 v6, 0xc0, v6
	v_and_or_b32 v82, v57, 24, v6
	ds_read_b128 v[6:9], v193
	s_waitcnt lgkmcnt(2)
	v_mfma_f32_32x32x16_bf16 v[34:49], v[14:17], v[10:13], v[34:49]
	v_lshl_add_u64 v[10:11], v[2:3], 0, s[28:29]
	v_lshl_add_u64 v[12:13], v[2:3], 0, s[24:25]
	global_load_dwordx4 v[62:65], v[10:11], off offset:256
	global_load_dwordx4 v[66:69], v[12:13], off offset:256
	v_add_co_u32_e32 v10, vcc, s19, v2
	s_mov_b32 s19, 0x60000
	s_nop 0
	v_addc_co_u32_e32 v11, vcc, 0, v3, vcc
	v_add_co_u32_e32 v2, vcc, s19, v2
	s_movk_i32 s19, 0x2000
	s_nop 0
	v_addc_co_u32_e32 v3, vcc, 0, v3, vcc
	global_load_dwordx4 v[70:73], v[10:11], off
	global_load_dwordx4 v[74:77], v[2:3], off
	v_add_co_u32_e32 v2, vcc, s19, v4
	s_waitcnt lgkmcnt(0)
	v_mfma_f32_32x32x16_bf16 v[18:33], v[6:9], v[58:61], v[18:33]
	v_addc_co_u32_e32 v3, vcc, 0, v5, vcc
	global_load_dwordx4 v[78:81], v[2:3], off
	v_lshlrev_b32_e32 v2, 1, v56
	v_and_b32_e32 v10, 32, v2
	ds_read_b128 v[2:5], v199
	v_and_b32_e32 v6, 0x100, v57
	v_or3_b32 v57, v82, v10, v6
	v_or_b32_e32 v10, 64, v0
	v_mad_u32_u24 v210, v176, s74, v10
	v_add_u32_e32 v211, s18, v210
	ds_read_b128 v[6:9], v211
	s_waitcnt lgkmcnt(1)
	v_mfma_f32_32x32x16_bf16 v[34:49], v[2:5], v[58:61], v[34:49]
	ds_read_b128 v[2:5], v184 offset:64
	v_or_b32_e32 v14, 0x60, v0
	v_add_u32_e32 v212, v10, v55
	v_mad_u32_u24 v214, v176, s74, v14
	v_add_u32_e32 v213, s18, v212
	v_add_u32_e32 v215, s18, v214
	ds_read_b128 v[10:13], v213
	ds_read_b128 v[58:61], v184 offset:96
	s_waitcnt lgkmcnt(2)
	v_mfma_f32_32x32x16_bf16 v[18:33], v[6:9], v[2:5], v[18:33]
	ds_read_b128 v[6:9], v215
	v_add_u32_e32 v216, v14, v55
	v_add_u32_e32 v217, s18, v216
	ds_read_b128 v[82:85], v217
	s_waitcnt vmcnt(0)
	s_waitcnt vmcnt(4)
	ds_write_b128 v185, v[62:65] offset:16384
	s_waitcnt vmcnt(3)
	ds_write_b128 v186, v[66:69] offset:16384
	s_waitcnt vmcnt(2)
	ds_write_b128 v187, v[70:73] offset:50176
	s_waitcnt vmcnt(1)
	ds_write_b128 v187, v[74:77] offset:58880
	s_waitcnt lgkmcnt(7)
	v_mfma_f32_32x32x16_bf16 v[34:49], v[10:13], v[2:5], v[34:49]
	v_add_u32_e32 v182, s17, v57
	s_waitcnt vmcnt(0)
	ds_write_b128 v219, v[78:81]
	s_waitcnt lgkmcnt(0)
	s_barrier
	v_mfma_f32_32x32x16_bf16 v[18:33], v[6:9], v[58:61], v[18:33]
	v_mov_b64_e32 v[2:3], s[76:77]
	v_mov_b64_e32 v[16:17], s[90:91]
	v_mov_b64_e32 v[4:5], s[78:79]
	v_mov_b64_e32 v[6:7], s[80:81]
	v_mov_b64_e32 v[8:9], s[82:83]
	v_mov_b64_e32 v[10:11], s[84:85]
	v_mov_b64_e32 v[12:13], s[86:87]
	v_mfma_f32_32x32x16_bf16 v[34:49], v[82:85], v[58:61], v[34:49]
	s_nop 3
	v_max_f32_e32 v55, v19, v19
	v_max_f32_e32 v58, v18, v18
	v_max_f32_e32 v55, v58, v55
	v_max3_f32 v55, v55, v20, v21
	v_max3_f32 v55, v55, v22, v23
	v_max3_f32 v55, v55, v24, v25
	v_max3_f32 v55, v55, v26, v27
	v_max3_f32 v55, v55, v28, v29
	v_max3_f32 v55, v55, v30, v31
	v_max3_f32 v55, v55, v32, v33
	v_max3_f32 v55, v55, v34, v35
	v_max3_f32 v55, v55, v36, v37
	v_max3_f32 v55, v55, v38, v39
	v_max3_f32 v55, v55, v40, v41
	v_max3_f32 v55, v55, v42, v43
	v_max3_f32 v55, v55, v44, v45
	v_max3_f32 v55, v55, v46, v47
	v_max3_f32 v55, v55, v48, v49
	v_mov_b32_e32 v58, v55
	s_nop 1
	v_permlane32_swap_b32_e32 v55, v58
	v_max_f32_e32 v58, v58, v58
	v_max_f32_e32 v55, v55, v55
	v_max_f32_e32 v55, v55, v58
	v_add_f32_e32 v58, 0x7149f2ca, v55
	v_cmp_ge_f32_e32 vcc, s21, v58
	s_cmp_eq_u64 vcc, exec
	v_max_f32_e32 v54, 0xf149f2ca, v55
	s_cselect_b64 vcc, -1, 0
	v_cndmask_b32_e32 v229, v54, v205, vcc
	v_sub_f32_e32 v55, 0xf149f2ca, v54
	v_mul_f32_e32 v54, 0xbdd53b94, v229
	v_fmamk_f32 v18, v18, 0x3dd53b94, v54
	v_exp_f32_e32 v66, v18
	v_fmamk_f32 v18, v19, 0x3dd53b94, v54
	v_exp_f32_e32 v67, v18
	v_fmamk_f32 v18, v20, 0x3dd53b94, v54
	v_exp_f32_e32 v68, v18
	v_fmamk_f32 v18, v21, 0x3dd53b94, v54
	v_exp_f32_e32 v69, v18
	v_fmamk_f32 v18, v22, 0x3dd53b94, v54
	v_exp_f32_e32 v70, v18
	v_fmamk_f32 v18, v23, 0x3dd53b94, v54
	v_exp_f32_e32 v71, v18
	v_fmamk_f32 v18, v24, 0x3dd53b94, v54
	v_exp_f32_e32 v72, v18
	v_fmamk_f32 v18, v25, 0x3dd53b94, v54
	v_exp_f32_e32 v73, v18
	v_fmamk_f32 v18, v26, 0x3dd53b94, v54
	v_exp_f32_e32 v74, v18
	v_fmamk_f32 v18, v27, 0x3dd53b94, v54
	v_exp_f32_e32 v75, v18
	v_fmamk_f32 v18, v28, 0x3dd53b94, v54
	v_mul_f32_e32 v55, 0x3dd53b94, v55
	v_exp_f32_e32 v76, v18
	v_fmamk_f32 v18, v29, 0x3dd53b94, v54
	v_exp_f32_e32 v55, v55
	v_exp_f32_e32 v77, v18
	v_fmamk_f32 v18, v30, 0x3dd53b94, v54
	v_exp_f32_e32 v78, v18
	v_fmamk_f32 v18, v31, 0x3dd53b94, v54
	v_exp_f32_e32 v79, v18
	v_fmamk_f32 v18, v32, 0x3dd53b94, v54
	v_exp_f32_e32 v80, v18
	v_and_b32_e32 v18, 7, v56
	v_pk_fma_f32 v[96:97], v[48:49], s[36:37], v[54:55] op_sel_hi:[1,0,0]
	v_pk_fma_f32 v[94:95], v[46:47], s[36:37], v[54:55] op_sel_hi:[1,0,0]
	v_pk_fma_f32 v[92:93], v[44:45], s[36:37], v[54:55] op_sel_hi:[1,0,0]
	v_pk_fma_f32 v[90:91], v[42:43], s[36:37], v[54:55] op_sel_hi:[1,0,0]
	v_pk_fma_f32 v[88:89], v[40:41], s[36:37], v[54:55] op_sel_hi:[1,0,0]
	v_pk_fma_f32 v[86:87], v[38:39], s[36:37], v[54:55] op_sel_hi:[1,0,0]
	v_pk_fma_f32 v[84:85], v[36:37], s[36:37], v[54:55] op_sel_hi:[1,0,0]
	v_pk_fma_f32 v[82:83], v[34:35], s[36:37], v[54:55] op_sel_hi:[1,0,0]
	v_fmac_f32_e32 v54, 0x3dd53b94, v33
	v_lshl_or_b32 v168, v18, 4, v168
	v_lshl_add_u64 v[18:19], v[50:51], 0, s[2:3]
	v_exp_f32_e32 v81, v54
	v_lshlrev_b64 v[170:171], 12, v[18:19]
	v_and_b32_e32 v18, 15, v56
	s_addk_i32 s17, 0x4000
	v_lshlrev_b32_e32 v18, 4, v18
	v_mov_b64_e32 v[14:15], s[88:89]
	v_cndmask_b32_e64 v220, v55, 1.0, vcc
	v_add_u32_e32 v181, s17, v57
	v_or3_b32 v170, v170, s20, v18
	v_mov_b64_e32 v[64:65], v[16:17]
	v_mov_b64_e32 v[48:49], v[16:17]
	v_mov_b64_e32 v[32:33], v[16:17]
	v_mov_b64_e32 v[62:63], v[14:15]
	v_mov_b64_e32 v[60:61], v[12:13]
	v_mov_b64_e32 v[58:59], v[10:11]
	v_mov_b64_e32 v[56:57], v[8:9]
	v_mov_b64_e32 v[54:55], v[6:7]
	v_mov_b64_e32 v[52:53], v[4:5]
	v_mov_b64_e32 v[50:51], v[2:3]
	v_mov_b64_e32 v[46:47], v[14:15]
	v_mov_b64_e32 v[44:45], v[12:13]
	v_mov_b64_e32 v[42:43], v[10:11]
	v_mov_b64_e32 v[40:41], v[8:9]
	v_mov_b64_e32 v[38:39], v[6:7]
	v_mov_b64_e32 v[36:37], v[4:5]
	v_mov_b64_e32 v[34:35], v[2:3]
	v_mov_b64_e32 v[30:31], v[14:15]
	v_mov_b64_e32 v[28:29], v[12:13]
	v_mov_b64_e32 v[26:27], v[10:11]
	v_mov_b64_e32 v[24:25], v[8:9]
	v_mov_b64_e32 v[22:23], v[6:7]
	v_mov_b64_e32 v[20:21], v[4:5]
	v_mov_b64_e32 v[18:19], v[2:3]
	.p2align 6

; __device__ __forceinline__ int crow(int r, int hi) { return (r & 3) + 8 * (r >> 2) + 4 * hi; }
; __device__ __forceinline__ void na_unit(const bf16_t* __restrict__ QKV, bf16_t* __restrict__ O, const float* __restrict__ rpb, int tok0, int rows, int g4, int h, char* lds) {
;     ...
;   for (int t = 0; t < nt; ++t) {
;     const int buf = t & 1, kr = krlo + t;
;     if (t + 1 < nt) { sk = *(const bf16x8*)(kg + (size_t)(t + 1) * 64 * 3072); sv = *(const bf16x8*)(kg + (size_t)(t + 1) * 64 * 3072 + 1024); }
;     if (kr >= r0w && kr <= r0w + 7) {
;       const char* Ks = lds + OFF_K + buf * SHM_K;
;       f32x16 p0 = {}, p1 = {};
; #pragma unroll
;       for (int d0 = 0; d0 < 4; ++d0) { const int cb = (d0 * 16 + hi * 8) * 2;
;         const bf16x8 b0 = *reinterpret_cast<const bf16x8*>(Ks + r32 * 144 + cb), b1 = *reinterpret_cast<const bf16x8*>(Ks + (32 + r32) * 144 + cb);
;         p0 = __builtin_amdgcn_mfma_f32_32x32x16_bf16(b0, qf[d0], p0, 0, 0, 0); p1 = __builtin_amdgcn_mfma_f32_32x32x16_bf16(b1, qf[d0], p1, 0, 0, 0); }
;       const float* Tr = T + (kr - qr + 7) * 128 + tb;
; #pragma unroll
;       for (int r = 0; r < 16; ++r) { const int ko = (r & 3) + 8 * (r >> 2), kc = ko + 4 * hi;
;         const bool v0 = (kc >= c0) && (kc <= c0 + 15), v1 = (kc + 32 >= c0) && (kc + 32 <= c0 + 15);
;         p0[r] = v0 ? fmaf(p0[r], 0.125f, Tr[ko]) : -1e30f; p1[r] = v1 ? fmaf(p1[r], 0.125f, Tr[ko + 32]) : -1e30f; }
;       float mn, al; bf16x8 pa0, pa1, pa2, pa3;
;       partialSM<64>(p0, p1, m_reg, mn, al);
;       finishSM(p0, p1, al, l_reg, pa0, pa1, pa2, pa3);
;       if (__any(al < 1.f)) { if (hi == 0) al_l[r32] = al; asm volatile("s_waitcnt lgkmcnt(0)" ::: "memory");
; #pragma unroll
;         for (int d = 0; d < 2; ++d)
; #pragma unroll
;           for (int r = 0; r < 16; ++r) o[d][r] *= al_l[crow(r, hi)]; }
;       const int vb = vb0 + buf * 16384;
;       pv_one<0>(o[0], vb, pa0, pa1, pa2, pa3); pv_one<1>(o[1], vb, pa0, pa1, pa2, pa3);
;     }
;     if (t + 1 < nt) { *(bf16x8*)(lds + OFF_K + (buf ^ 1) * SHM_K + kst) = sk; *(bf16x8*)(lds + OFF_V + (buf ^ 1) * 16384 + vst) = sv; }
;     __syncthreads();
;   }
.LBB0_385:
	s_add_i32 s20, s20, 1
	s_mov_b64 s[24:25], 0x60000
	v_lshl_add_u64 v[106:107], v[106:107], 0, s[24:25]
	s_cmp_eq_u32 s12, s20
	v_add_u32_e32 v116, 0x200, v116
	s_waitcnt lgkmcnt(0)
	s_barrier
	s_cbranch_scc1 .LBB0_461
	.p2align 6

; template <int DQK> __device__ __forceinline__ void qkt(f32x16& p0, f32x16& p1, const bf16_t* Ks, const char* KRs, const char* QRw, const bf16x8* qr, int r32, int hi) {
;   p0 = f32x16{}; p1 = f32x16{};
; #pragma unroll
;   for (int d0 = 0; d0 < 8; ++d0) { int cb = (d0 * 16 + hi * 8) * 2;
;     bf16x8 b0 = *reinterpret_cast<const bf16x8*>((const char*)Ks + KSWZ(r32, cb));
;     bf16x8 b1 = *reinterpret_cast<const bf16x8*>((const char*)Ks + KSWZ(32 + r32, cb));
;     p0 = __builtin_amdgcn_mfma_f32_32x32x16_bf16(b0, qr[d0], p0, 0, 0, 0);
;     p1 = __builtin_amdgcn_mfma_f32_32x32x16_bf16(b1, qr[d0], p1, 0, 0, 0); }
; template <int DQK, int LDK> ...
;     ...
;   const bf16_t* Qw = Qb + (long)(wid * QBLK + r32) * LDQ + hi * 8;
; #pragma unroll
;   for (int d0 = 0; d0 < NQ; ++d0) qr[d0] = *reinterpret_cast<const bf16x8*>(Qw + d0 * 16);
;     ...
;   SLOAD(SE, 0); asm volatile("s_waitcnt vmcnt(0)" ::: "memory"); SWRITE(0, SE); __syncthreads();
;   qkt<DQK>(pA0, pA1, K_lds, KR_lds, QRw, qr, r32, hi); partialSM<DQK>(pA0, pA1, m_reg, mnA, alA);
.LBB0_477:
	s_lshl_b32 s2, s7, 5
	s_cmpk_lt_i32 s7, 0x200
	s_cselect_b32 s5, 0xffffe000, s71
	s_movk_i32 s8, 0x4000
	s_cselect_b32 s3, 31, 7
	s_cselect_b32 s4, 5, 3
	s_cselect_b32 s8, s8, 0xffffc000
	s_cselect_b32 s15, 0x7d, 29
	s_and_b32 s2, s2, s5
	s_lshr_b32 s4, s7, s4
	s_add_i32 s2, s2, s8
	s_and_b32 s9, s7, s3
	s_and_b32 s14, s4, 7
	s_ashr_i32 s3, s2, 31
	s_mul_i32 s8, s2, 0xc00
	s_mul_hi_i32 s5, s2, 0xc00
	s_add_u32 s8, s56, s8
	s_addc_u32 s5, s57, s5
	s_lshl_b32 s4, s4, 6
	s_and_b32 s17, s4, 0x100
	s_add_u32 s4, s8, s17
	s_waitcnt vmcnt(0)
	v_mov_b32_e32 v98, v200
	s_addc_u32 s5, s5, 0
	s_lshl_b32 s8, s9, 8
	s_movk_i32 s21, 0x600
	v_ashrrev_i32_e32 v50, 4, v98
	v_lshlrev_b32_e32 v210, 3, v98
	s_add_i32 s26, s8, s2
	v_and_b32_e32 v72, 0x78, v210
	v_mad_i64_i32 v[2:3], s[8:9], v50, s21, 0
	v_add_u32_e32 v21, 32, v50
	v_or_b32_e32 v2, v2, v72
	s_ashr_i32 s27, s26, 31
	s_mul_i32 s18, s26, 0xc00
	s_waitcnt vmcnt(4)
	v_lshl_add_u64 v[10:11], v[2:3], 1, s[4:5]
	v_mad_i64_i32 v[6:7], s[8:9], v21, s21, 0
	s_mul_hi_i32 s16, s26, 0xc00
	global_load_dwordx4 v[2:5], v[10:11], off offset:2560
	s_add_u32 s8, s56, s18
	v_or_b32_e32 v6, v6, v72
	s_addc_u32 s16, s57, s16
	s_lshl_b32 s9, s14, 7
	s_lshl_b32 s14, s14, 8
	s_waitcnt vmcnt(1)
	v_lshl_add_u64 v[14:15], v[6:7], 1, s[4:5]
	v_readfirstlane_b32 s20, v98
	s_add_u32 s18, s8, s14
	global_load_dwordx4 v[6:9], v[14:15], off offset:2560
	s_nop 0
	global_load_dwordx4 v[10:13], v[10:11], off offset:2048
	s_nop 0
	global_load_dwordx4 v[14:17], v[14:15], off offset:2048
	s_addc_u32 s19, s16, 0
	s_ashr_i32 s8, s20, 6
	v_and_b32_e32 v211, 31, v98
	s_lshl_b32 s34, s8, 5
	v_bfe_u32 v212, v98, 5, 1
	v_or_b32_e32 v0, s34, v211
	v_mov_b64_e32 v[18:19], s[18:19]
	v_mad_i64_i32 v[18:19], s[18:19], v0, s23, v[18:19]
	v_lshlrev_b32_e32 v0, 4, v212
	v_lshl_add_u64 v[18:19], v[18:19], 0, v[0:1]
	global_load_dwordx4 v[158:161], v[18:19], off
	global_load_dwordx4 v[154:157], v[18:19], off offset:32
	global_load_dwordx4 v[150:153], v[18:19], off offset:64
	global_load_dwordx4 v[146:149], v[18:19], off offset:96
	global_load_dwordx4 v[142:145], v[18:19], off offset:128
	global_load_dwordx4 v[138:141], v[18:19], off offset:160
	global_load_dwordx4 v[134:137], v[18:19], off offset:192
	global_load_dwordx4 v[130:133], v[18:19], off offset:224
	v_and_b32_e32 v20, 0xfffff0, v50
	v_lshlrev_b32_e32 v22, 1, v50
	v_lshrrev_b32_e32 v23, 1, v50
	v_and_b32_e32 v25, 3, v50
	v_and_or_b32 v22, v22, 8, v20
	v_and_or_b32 v23, v23, 4, v25
	v_and_b32_e32 v25, 0xfffff0, v21
	v_lshlrev_b32_e32 v21, 1, v21
	v_bfe_u32 v24, v210, 5, 2
	v_lshrrev_b32_e32 v22, 1, v22
	v_and_or_b32 v21, v21, 8, v25
	v_lshlrev_b32_e32 v20, 1, v72
	v_or_b32_e32 v22, v22, v24
	v_lshrrev_b32_e32 v21, 1, v21
	v_lshlrev_b32_e32 v23, 6, v23
	v_and_b32_e32 v26, 48, v20
	v_lshlrev_b32_e32 v22, 9, v22
	v_or_b32_e32 v21, v21, v24
	v_or3_b32 v22, v22, v23, v26
	v_lshlrev_b32_e32 v21, 9, v21
	v_or3_b32 v21, v21, v23, v26
	v_add_u32_e32 v219, 0, v22
	s_waitcnt vmcnt(0)
	v_add_u32_e32 v220, 0, v21
	v_and_b32_e32 v213, 63, v98
	s_and_b32 s14, s20, 0x3fffffc0
	s_lshl_b32 s14, s14, 2
	s_add_i32 s14, s14, 0
	s_add_i32 s14, s14, 0x15000
	s_cmp_lg_u32 0, -1
	s_cselect_b32 s20, 0, 0
	v_ashrrev_i32_e32 v51, 31, v50
	s_mov_b32 s76, s77
	s_mov_b32 s78, s77
	s_mov_b32 s79, s77
	s_mov_b32 s80, s77
	s_mov_b32 s81, s77
	s_mov_b32 s82, s77
	s_mov_b32 s83, s77
	s_mov_b32 s84, s77
	s_mov_b32 s85, s77
	s_mov_b32 s86, s77
	s_mov_b32 s87, s77
	s_mov_b32 s88, s77
	s_mov_b32 s89, s77
	s_mov_b32 s90, s77
	s_mov_b32 s91, s77
	s_mov_b32 s16, 1
	v_cmp_gt_u32_e64 s[40:41], 32, v213
	v_lshl_add_u32 v214, v211, 2, s14
	v_mov_b32_e32 v215, 0
	s_waitcnt vmcnt(11)
	ds_write_b128 v219, v[2:5]
	v_mad_u64_u32 v[2:3], s[18:19], v50, s75, v[20:21]
	v_add_u32_e32 v221, 0, v2
	v_mad_u32_u24 v2, v211, s75, v0
	v_add_u32_e32 v218, 0, v2
	s_waitcnt vmcnt(10)
	ds_write_b128 v220, v[6:9]
	s_waitcnt vmcnt(9)
	ds_write_b128 v221, v[10:13] offset:32768
	s_waitcnt vmcnt(8)
	ds_write_b128 v221, v[14:17] offset:41472
	s_waitcnt lgkmcnt(0)
	s_barrier
	ds_read_b128 v[2:5], v218 offset:32768
	ds_read_b128 v[6:9], v218 offset:32800
	s_waitcnt vmcnt(7) lgkmcnt(1)
	v_mfma_f32_32x32x16_bf16 v[18:33], v[2:5], v[158:161], 0
	ds_read_b128 v[2:5], v218 offset:41472
	ds_read_b128 v[10:13], v218 offset:41504
	v_lshlrev_b32_e32 v16, 4, v98
	v_lshlrev_b32_e32 v17, 3, v213
	s_waitcnt lgkmcnt(1)
	v_mfma_f32_32x32x16_bf16 v[34:49], v[2:5], v[158:161], 0
	s_waitcnt vmcnt(6)
	v_mfma_f32_32x32x16_bf16 v[18:33], v[6:9], v[154:157], v[18:33]
	ds_read_b128 v[2:5], v218 offset:32832
	ds_read_b128 v[6:9], v218 offset:32864
	s_waitcnt lgkmcnt(2)
	v_mfma_f32_32x32x16_bf16 v[34:49], v[10:13], v[154:157], v[34:49]
	s_waitcnt vmcnt(5) lgkmcnt(1)
	v_mfma_f32_32x32x16_bf16 v[18:33], v[2:5], v[150:153], v[18:33]
	ds_read_b128 v[2:5], v218 offset:41536
	ds_read_b128 v[10:13], v218 offset:41568
	s_waitcnt lgkmcnt(1)
	v_mfma_f32_32x32x16_bf16 v[34:49], v[2:5], v[150:153], v[34:49]
	ds_read_b128 v[2:5], v218 offset:32896
	s_waitcnt vmcnt(4)
	v_mfma_f32_32x32x16_bf16 v[18:33], v[6:9], v[146:149], v[18:33]
	s_waitcnt lgkmcnt(1)
	v_mfma_f32_32x32x16_bf16 v[34:49], v[10:13], v[146:149], v[34:49]
	ds_read_b128 v[6:9], v218 offset:41600
	ds_read_b128 v[10:13], v218 offset:32928
	s_waitcnt vmcnt(3) lgkmcnt(2)
	v_mfma_f32_32x32x16_bf16 v[18:33], v[2:5], v[142:145], v[18:33]
	v_add_u32_e32 v2, 64, v50
	v_mad_i64_i32 v[14:15], s[18:19], v2, s21, 0
	v_or_b32_e32 v14, v14, v72
	ds_read_b128 v[2:5], v218 offset:41632
	s_waitcnt lgkmcnt(2)
; #define SWAIT() do { if constexpr (SD == 1) asm volatile("s_waitcnt vmcnt(0)" ::: "memory"); else asm volatile("s_waitcnt vmcnt(4)" ::: "memory"); } while (0)
; template <int DQK> __device__ __forceinline__ void partialSM(f32x16& p0, f32x16& p1, float& m_reg, float& mn, float& alpha) {
;   constexpr float SCALE = (DQK == 192) ? 0.07216878364870322f : (DQK == 64 ? 1.0f : 0.08838834764831845f);
;   constexpr float C = SCALE * 1.4426950408889634f;
;   float pmax = p0[0];
; #pragma unroll
;   for (int r = 1; r < 16; ++r) pmax = fmaxf(pmax, p0[r]);
; #pragma unroll
;   for (int r = 0; r < 16; ++r) pmax = fmaxf(pmax, p1[r]);
;   { auto rr = __builtin_amdgcn_permlane32_swap(__float_as_uint(pmax), __float_as_uint(pmax), false, false);
;     pmax = fmaxf(__uint_as_float(rr[0]), __uint_as_float(rr[1])); }
;   if (__builtin_expect(__all(pmax - m_reg <= THR / SCALE), 1)) { mn = m_reg; alpha = 1.f; }
;   else { mn = fmaxf(m_reg, pmax); alpha = __builtin_amdgcn_exp2f((m_reg - mn) * C); m_reg = mn; }
;   float mnC = -mn * C;
; #pragma unroll
;   for (int r = 0; r < 16; ++r) p0[r] = fmaf(p0[r], C, mnC);
; #pragma unroll
;   for (int r = 0; r < 16; ++r) p1[r] = fmaf(p1[r], C, mnC);
; #pragma unroll
;   for (int r = 0; r < 16; ++r) p0[r] = __builtin_amdgcn_exp2f(p0[r]);
; }
; template <int DQK, int LDK> ...
;     ...
;   qkt<DQK>(pA0, pA1, K_lds, KR_lds, QRw, qr, r32, hi); partialSM<DQK>(pA0, pA1, m_reg, mnA, alA);
;   SLOAD(SO, KVBLK); if constexpr (SD == 2) { if (2 < NT) SLOAD(SE, 2 * KVBLK); }
;   SWAIT(); SWRITE(1, SO); __syncthreads();
	v_mfma_f32_32x32x16_bf16 v[34:49], v[6:9], v[142:145], v[34:49]
	v_add_u32_e32 v8, 0x60, v50
	v_mad_i64_i32 v[8:9], s[18:19], v8, s21, 0
	v_or_b32_e32 v8, v8, v72
	v_lshl_add_u64 v[6:7], v[14:15], 1, s[4:5]
	v_lshl_add_u64 v[8:9], v[8:9], 1, s[4:5]
	global_load_dwordx4 v[52:55], v[6:7], off offset:2560
	global_load_dwordx4 v[56:59], v[8:9], off offset:2560
	global_load_dwordx4 v[60:63], v[6:7], off offset:2048
	global_load_dwordx4 v[64:67], v[8:9], off offset:2048
	ds_read_b128 v[6:9], v218 offset:32960
	s_waitcnt vmcnt(6) lgkmcnt(2)
	v_mfma_f32_32x32x16_bf16 v[18:33], v[10:13], v[138:141], v[18:33]
	v_and_b32_e32 v10, 0xc0, v16
	s_waitcnt lgkmcnt(1)
	v_mfma_f32_32x32x16_bf16 v[34:49], v[2:5], v[138:141], v[34:49]
	v_lshlrev_b32_e32 v3, 1, v98
	v_and_or_b32 v2, v17, 24, v10
	v_and_b32_e32 v3, 32, v3
	v_and_b32_e32 v4, 0x100, v17
	v_or3_b32 v99, v2, v3, v4
	ds_read_b128 v[2:5], v218 offset:41664
	ds_read_b128 v[10:13], v218 offset:32992
	ds_read_b128 v[68:71], v218 offset:41696
	s_waitcnt vmcnt(5) lgkmcnt(3)
	v_mfma_f32_32x32x16_bf16 v[18:33], v[6:9], v[134:137], v[18:33]
	v_add_u32_e32 v217, s20, v99
	s_waitcnt lgkmcnt(2)
	v_mfma_f32_32x32x16_bf16 v[34:49], v[2:5], v[134:137], v[34:49]
	s_waitcnt vmcnt(4) lgkmcnt(1)
	v_mfma_f32_32x32x16_bf16 v[18:33], v[10:13], v[130:133], v[18:33]
	v_mov_b64_e32 v[2:3], s[76:77]
	v_mov_b64_e32 v[16:17], s[90:91]
	v_mov_b64_e32 v[4:5], s[78:79]
	v_mov_b64_e32 v[6:7], s[80:81]
	v_mov_b64_e32 v[8:9], s[82:83]
	v_mov_b64_e32 v[10:11], s[84:85]
	v_mov_b64_e32 v[12:13], s[86:87]
	s_waitcnt lgkmcnt(0)
	v_mfma_f32_32x32x16_bf16 v[34:49], v[68:71], v[130:133], v[34:49]
	s_nop 2
	v_max_f32_e32 v68, v19, v19
	v_max_f32_e32 v69, v18, v18
	v_max_f32_e32 v68, v69, v68
	v_max3_f32 v68, v68, v20, v21
	v_max3_f32 v68, v68, v22, v23
	v_max3_f32 v68, v68, v24, v25
	v_max3_f32 v68, v68, v26, v27
	v_max3_f32 v68, v68, v28, v29
	v_max3_f32 v68, v68, v30, v31
	v_max3_f32 v68, v68, v32, v33
	v_max3_f32 v68, v68, v34, v35
	v_max3_f32 v68, v68, v36, v37
	v_max3_f32 v68, v68, v38, v39
	v_max3_f32 v68, v68, v40, v41
	v_max3_f32 v68, v68, v42, v43
	v_max3_f32 v68, v68, v44, v45
	v_max3_f32 v68, v68, v46, v47
	v_max3_f32 v73, v68, v48, v49
	v_add_u32_e32 v68, 0xa0, v50
	v_mad_i64_i32 v[68:69], s[18:19], v68, s21, 0
	v_add_u32_e32 v70, 0x80, v50
	v_or_b32_e32 v68, v68, v72
	v_mad_i64_i32 v[70:71], s[18:19], v70, s21, 0
	v_lshl_add_u64 v[68:69], v[68:69], 1, s[4:5]
	v_or_b32_e32 v70, v70, v72
	v_lshl_add_u64 v[70:71], v[70:71], 1, s[4:5]
	global_load_dwordx4 v[166:169], v[68:69], off offset:2048
	global_load_dwordx4 v[170:173], v[68:69], off offset:2560
	global_load_dwordx4 v[174:177], v[70:71], off offset:2048
	global_load_dwordx4 v[162:165], v[70:71], off offset:2560
	v_mov_b32_e32 v74, v73
	s_nop 1
	v_permlane32_swap_b32_e32 v73, v74
	v_max_f32_e32 v68, v74, v74
	v_max_f32_e32 v69, v73, v73
	v_max_f32_e32 v68, v69, v68
	v_add_f32_e32 v69, 0x7149f2ca, v68
	v_cmp_ge_f32_e32 vcc, s22, v69
	s_cmp_eq_u64 vcc, exec
	s_waitcnt vmcnt(4)
	s_waitcnt vmcnt(7)
	ds_write_b128 v219, v[52:55] offset:16384
	s_waitcnt vmcnt(6)
	ds_write_b128 v220, v[56:59] offset:16384
	s_waitcnt vmcnt(5)
	ds_write_b128 v221, v[60:63] offset:50176
	s_waitcnt vmcnt(4)
	ds_write_b128 v221, v[64:67] offset:58880
	v_max_f32_e32 v52, 0xf149f2ca, v68
	s_cselect_b64 vcc, -1, 0
	v_cndmask_b32_e32 v226, v52, v205, vcc
	v_sub_f32_e32 v53, 0xf149f2ca, v52
	v_mul_f32_e32 v52, 0xbe0293ee, v226
	v_fmamk_f32 v18, v18, 0x3e0293ee, v52
	v_exp_f32_e32 v66, v18
	v_fmamk_f32 v18, v19, 0x3e0293ee, v52
	v_exp_f32_e32 v67, v18
	v_fmamk_f32 v18, v20, 0x3e0293ee, v52
	v_exp_f32_e32 v68, v18
	v_fmamk_f32 v18, v21, 0x3e0293ee, v52
	v_exp_f32_e32 v69, v18
	v_fmamk_f32 v18, v22, 0x3e0293ee, v52
	v_exp_f32_e32 v70, v18
	v_fmamk_f32 v18, v23, 0x3e0293ee, v52
	v_exp_f32_e32 v71, v18
	v_fmamk_f32 v18, v24, 0x3e0293ee, v52
	v_exp_f32_e32 v72, v18
	v_fmamk_f32 v18, v25, 0x3e0293ee, v52
	v_exp_f32_e32 v73, v18
	v_fmamk_f32 v18, v26, 0x3e0293ee, v52
	v_exp_f32_e32 v74, v18
	v_fmamk_f32 v18, v27, 0x3e0293ee, v52
	v_exp_f32_e32 v75, v18
	v_fmamk_f32 v18, v28, 0x3e0293ee, v52
	v_mul_f32_e32 v53, 0x3e0293ee, v53
	v_exp_f32_e32 v76, v18
	v_fmamk_f32 v18, v29, 0x3e0293ee, v52
	v_exp_f32_e32 v53, v53
	v_exp_f32_e32 v77, v18
	v_fmamk_f32 v18, v30, 0x3e0293ee, v52
	v_exp_f32_e32 v78, v18
	v_fmamk_f32 v18, v31, 0x3e0293ee, v52
	v_exp_f32_e32 v79, v18
	v_fmamk_f32 v18, v32, 0x3e0293ee, v52
	v_exp_f32_e32 v80, v18
	v_lshl_add_u64 v[18:19], v[50:51], 0, s[2:3]
	v_pk_fma_f32 v[96:97], v[48:49], s[94:95], v[52:53] op_sel_hi:[1,0,0]
	v_pk_fma_f32 v[94:95], v[46:47], s[94:95], v[52:53] op_sel_hi:[1,0,0]
	v_pk_fma_f32 v[92:93], v[44:45], s[94:95], v[52:53] op_sel_hi:[1,0,0]
	v_pk_fma_f32 v[90:91], v[42:43], s[94:95], v[52:53] op_sel_hi:[1,0,0]
	v_pk_fma_f32 v[88:89], v[40:41], s[94:95], v[52:53] op_sel_hi:[1,0,0]
	v_pk_fma_f32 v[86:87], v[38:39], s[94:95], v[52:53] op_sel_hi:[1,0,0]
	v_pk_fma_f32 v[84:85], v[36:37], s[94:95], v[52:53] op_sel_hi:[1,0,0]
	v_pk_fma_f32 v[82:83], v[34:35], s[94:95], v[52:53] op_sel_hi:[1,0,0]
	v_fmac_f32_e32 v52, 0x3e0293ee, v33
	v_mad_u64_u32 v[20:21], s[2:3], v18, s23, 0
	v_and_b32_e32 v18, 15, v98
	v_exp_f32_e32 v81, v52
	v_lshlrev_b32_e32 v18, 4, v18
	v_readlane_b32 s2, v253, 40
	v_mad_i32_i24 v19, v19, s23, v21
	v_or3_b32 v18, v20, s17, v18
	v_readlane_b32 s3, v253, 41
	v_mov_b64_e32 v[14:15], s[88:89]
	v_cndmask_b32_e64 v222, v53, 1.0, vcc
	s_addk_i32 s20, 0x4000
	v_lshl_add_u64 v[198:199], s[2:3], 0, v[18:19]
	v_mov_b64_e32 v[64:65], v[16:17]
	v_mov_b64_e32 v[48:49], v[16:17]
	v_mov_b64_e32 v[32:33], v[16:17]
	v_add_u32_e32 v216, s20, v99
	v_mov_b64_e32 v[62:63], v[14:15]
	v_mov_b64_e32 v[60:61], v[12:13]
	v_mov_b64_e32 v[58:59], v[10:11]
	v_mov_b64_e32 v[56:57], v[8:9]
	v_mov_b64_e32 v[54:55], v[6:7]
	v_mov_b64_e32 v[52:53], v[4:5]
	v_mov_b64_e32 v[50:51], v[2:3]
	v_mov_b64_e32 v[46:47], v[14:15]
	v_mov_b64_e32 v[44:45], v[12:13]
	v_mov_b64_e32 v[42:43], v[10:11]
	v_mov_b64_e32 v[40:41], v[8:9]
	v_mov_b64_e32 v[38:39], v[6:7]
	v_mov_b64_e32 v[36:37], v[4:5]
	v_mov_b64_e32 v[34:35], v[2:3]
	v_mov_b64_e32 v[30:31], v[14:15]
	v_mov_b64_e32 v[28:29], v[12:13]
	v_mov_b64_e32 v[26:27], v[10:11]
	v_mov_b64_e32 v[24:25], v[8:9]
	v_mov_b64_e32 v[22:23], v[6:7]
	v_mov_b64_e32 v[20:21], v[4:5]
	v_mov_b64_e32 v[18:19], v[2:3]
	s_waitcnt lgkmcnt(0)
	s_barrier
	.p2align 6
